# sync points 72/96
# speedup vs baseline: 1.0036x; 1.0036x over previous
; template <bool INSYNC> DI void mlstm_phase(const Ctx& C, const bf16* PROJ, const f32x4* TAB, const bf16* PP, bf16* HF, bf16* HB, const XcdBarrier& xbar) {
;     ...
;         for (int c = 0; c < SEQ / 64; ++c) {
;             if (INSYNC && (c == 43 || c == 86)) xcd_barrier(xbar);
.LBB0_1403:
	s_mov_b32 s35, s22
	s_cmpk_lt_i32 s22, 0x60
	s_cbranch_scc1 .LBB0_1405
	s_cmpk_eq_i32 s35, 0x60
	s_cselect_b64 s[20:21], -1, 0
	s_cbranch_execz .LBB0_1406
	s_branch .LBB0_1407

; template <bool INSYNC> DI void mlstm_phase(const Ctx& C, const bf16* PROJ, const f32x4* TAB, const bf16* PP, bf16* HF, bf16* HB, const XcdBarrier& xbar) {
;     ...
;             if (INSYNC && (c == 43 || c == 86)) xcd_barrier(xbar);
.LBB0_1406:
	s_cmp_eq_u32 s35, 72
	s_cselect_b64 s[20:21], -1, 0
